# v64 with one scan-progress poll at the entry of the early P1b call (all aliased sequences past chunk 20) instead of one per unit
# speedup vs baseline: 1.0237x; 1.0017x over previous
.Lp1be_chk:
	s_cmpk_lt_u32 s83, 0x80
	s_cbranch_scc1 .LBB0_495
	s_waitcnt vmcnt(0) lgkmcnt(0)
	v_readlane_b32 s86, v254, 50
	v_readlane_b32 s87, v254, 51
	v_readlane_b32 s74, v255, 1
	v_readlane_b32 s78, v254, 62
	v_readlane_b32 s90, v254, 54
	v_readlane_b32 s92, v254, 52
	v_readlane_b32 s75, v255, 2
	v_readlane_b32 s79, v254, 63
	v_readlane_b32 s77, v254, 61
	v_readlane_b32 s82, v254, 58
	v_readlane_b32 s91, v254, 55
	v_readlane_b32 s93, v254, 53
	v_and_b32_e32 v0, 63, v179
	v_min_u32_e32 v0, 8, v0
	v_lshlrev_b32_e32 v0, 5, v0
	s_add_u32 s100, s74, 0x80000
	s_addc_u32 s101, s75, 0
	s_movk_i32 s99, 0x200
.Lp1be_spin:
	global_load_dword v1, v0, s[100:101] sc1
	s_waitcnt vmcnt(0)
	v_cmp_gt_u32_e32 vcc, 0xa8, v1
	s_cmp_eq_u64 vcc, 0
	s_cbranch_scc1 .Lp1be_go
	s_sleep 8
	s_add_i32 s99, s99, -1
	s_cmp_lg_u32 s99, 0
	s_cbranch_scc1 .Lp1be_spin
.Lp1be_go:
	s_addk_i32 s83, 0x380
	s_movk_i32 s80, 0x80
	s_mov_b32 s98, 1
	s_movk_i32 s99, 0x600
	s_movk_i32 s100, 0x5ff
	s_branch .Lp1be_entry
